# static s_setprio 1 for waves 4-7 in FoX and NSA unit loops, per-segment flips there deleted
# speedup vs baseline: 1.0020x; 1.0018x over previous
.LBB0_261:
	s_barrier
	v_readfirstlane_b32 s22, v160
	s_nop 3
	s_lshr_b32 s22, s22, 6
	s_cmp_ge_u32 s22, 4
	s_cbranch_scc0 .Lprio_done_fox
	s_setprio 1
.Lprio_done_fox:
	s_mov_b64 s[20:21], exec
	v_readlane_b32 s22, v254, 3
	v_readlane_b32 s23, v254, 4
	s_and_b64 s[22:23], s[20:21], s[22:23]
	s_mov_b64 exec, s[22:23]
	s_cbranch_execz .LBB0_265
	s_mov_b64 s[24:25], exec
	v_mbcnt_lo_u32_b32 v0, s24, 0
	v_mbcnt_hi_u32_b32 v0, s25, v0
	v_cmp_eq_u32_e32 vcc, 0, v0
	s_and_saveexec_b64 s[22:23], vcc
	s_cbranch_execz .LBB0_264
	s_bcnt1_i32_b64 s24, s[24:25]
	v_mov_b32_e32 v1, s24
	global_atomic_add v1, v97, v1, s[70:71] sc0

.LBB0_291:
	s_sub_i32 s26, s48, 63
	s_cmp_gt_i32 s26, s46
	s_mov_b32 s61, 0
	s_cbranch_scc1 .LBB0_300
	v_mov_b32_e32 v32, s47
	ds_read_b32 v32, v32
	s_mov_b32 s61, 1
	s_waitcnt lgkmcnt(0)
	v_add_f32_e32 v32, v115, v32
	v_cmp_lt_f32_e32 vcc, v32, v123
	s_cmp_eq_u64 vcc, exec
	s_cbranch_scc1 .LBB0_300
	s_add_i32 s61, s53, 0x100
	v_add_u32_e32 v44, s47, v98
	v_add_u32_e32 v32, 0xffffff04, v44
	v_add_u32_e32 v33, 0xffffff84, v44
	v_add_u32_e32 v36, 0xffffff24, v44
	v_add_u32_e32 v37, 0xffffffa4, v44
	v_add_u32_e32 v40, 0xffffff44, v44
	v_subrev_u32_e32 v41, 60, v44
	v_add_u32_e32 v45, 0xffffff64, v44
	v_subrev_u32_e32 v44, 28, v44
	v_add3_u32 v152, s61, v119, v120
	ds_read_b128 v[48:51], v32
	ds_read_b128 v[32:35], v33
	ds_read_b128 v[52:55], v36
	ds_read_b128 v[36:39], v37
	ds_read_b128 v[56:59], v40
	ds_read_b128 v[40:43], v41
	ds_read_b128 v[60:63], v45
	ds_read_b128 v[44:47], v44
	ds_read_b128 v[124:127], v152
	ds_read_b128 v[128:131], v152 offset:512
	ds_read_b128 v[132:135], v152 offset:2048
	ds_read_b128 v[136:139], v152 offset:2560
	ds_read_b128 v[140:143], v152 offset:4096
	ds_read_b128 v[144:147], v152 offset:4608
	ds_read_b128 v[148:151], v152 offset:6144
	ds_read_b128 v[152:155], v152 offset:6656
	s_waitcnt lgkmcnt(7)
	v_mfma_f32_32x32x16_bf16 v[48:63], v[124:127], v[64:67], v[48:63]
	s_waitcnt lgkmcnt(6)
	v_mfma_f32_32x32x16_bf16 v[32:47], v[128:131], v[64:67], v[32:47]
	s_waitcnt lgkmcnt(5)
	v_mfma_f32_32x32x16_bf16 v[48:63], v[132:135], v[68:71], v[48:63]
	s_waitcnt lgkmcnt(4)
	v_mfma_f32_32x32x16_bf16 v[32:47], v[136:139], v[68:71], v[32:47]
	s_waitcnt lgkmcnt(3)
	v_mfma_f32_32x32x16_bf16 v[48:63], v[140:143], v[72:75], v[48:63]
	s_waitcnt lgkmcnt(2)
	v_mfma_f32_32x32x16_bf16 v[32:47], v[144:147], v[72:75], v[32:47]
	s_waitcnt lgkmcnt(1)
	v_mfma_f32_32x32x16_bf16 v[48:63], v[148:151], v[76:79], v[48:63]
	s_waitcnt lgkmcnt(0)
	v_mfma_f32_32x32x16_bf16 v[32:47], v[152:155], v[76:79], v[32:47]
	s_cmp_le_i32 s48, s80
	s_cbranch_scc1 .LBB0_295
	v_add_u32_e32 v124, s48, v114
	v_subrev_u32_e32 v126, 31, v124
	v_subrev_u32_e32 v125, 63, v124
	v_cmp_le_i32_e32 vcc, v126, v96
	s_nop 4
	v_cndmask_b32_e32 v32, v108, v32, vcc
	v_cmp_lt_i32_e32 vcc, v125, v96
	s_nop 1
	v_cndmask_b32_e32 v49, v108, v49, vcc
	v_cmp_le_i32_e32 vcc, v125, v96
	v_subrev_u32_e32 v125, 30, v124
	s_nop 0
	v_cndmask_b32_e32 v48, v108, v48, vcc
	v_cmp_le_i32_e32 vcc, v125, v96
	v_subrev_u32_e32 v125, 61, v124
	s_nop 0
	v_cndmask_b32_e32 v33, v108, v33, vcc
	v_cmp_le_i32_e32 vcc, v125, v96
	v_subrev_u32_e32 v125, 29, v124
	s_nop 0
	v_cndmask_b32_e32 v50, v108, v50, vcc
	v_cmp_le_i32_e32 vcc, v125, v96
	v_subrev_u32_e32 v125, 60, v124
	s_nop 0
	v_cndmask_b32_e32 v34, v108, v34, vcc
	v_cmp_le_i32_e32 vcc, v125, v96
	v_subrev_u32_e32 v125, 28, v124
	s_nop 0
	v_cndmask_b32_e32 v51, v108, v51, vcc
	v_cmp_le_i32_e32 vcc, v125, v96
	v_subrev_u32_e32 v125, 55, v124
	s_nop 0
	v_cndmask_b32_e32 v35, v108, v35, vcc
	v_cmp_le_i32_e32 vcc, v125, v96
	v_subrev_u32_e32 v125, 23, v124
	s_nop 0
	v_cndmask_b32_e32 v52, v108, v52, vcc
	v_cmp_le_i32_e32 vcc, v125, v96
	v_subrev_u32_e32 v125, 54, v124
	s_nop 0
	v_cndmask_b32_e32 v36, v108, v36, vcc
	v_cmp_le_i32_e32 vcc, v125, v96
	v_subrev_u32_e32 v125, 22, v124
	s_nop 0
	v_cndmask_b32_e32 v53, v108, v53, vcc
	v_cmp_le_i32_e32 vcc, v125, v96
	v_subrev_u32_e32 v125, 53, v124
	s_nop 0
	v_cndmask_b32_e32 v37, v108, v37, vcc
	v_cmp_le_i32_e32 vcc, v125, v96
	v_subrev_u32_e32 v125, 21, v124
	s_nop 0
	v_cndmask_b32_e32 v54, v108, v54, vcc
	v_cmp_le_i32_e32 vcc, v125, v96
	v_subrev_u32_e32 v125, 52, v124
	s_nop 0
	v_cndmask_b32_e32 v38, v108, v38, vcc
	v_cmp_le_i32_e32 vcc, v125, v96
	v_subrev_u32_e32 v125, 20, v124
	s_nop 0
	v_cndmask_b32_e32 v55, v108, v55, vcc
	v_cmp_le_i32_e32 vcc, v125, v96
	v_subrev_u32_e32 v125, 47, v124
	s_nop 0
	v_cndmask_b32_e32 v39, v108, v39, vcc
	v_cmp_le_i32_e32 vcc, v125, v96
	v_add_u32_e32 v125, -15, v124
	s_nop 0
	v_cndmask_b32_e32 v56, v108, v56, vcc
	v_cmp_le_i32_e32 vcc, v125, v96
	v_subrev_u32_e32 v125, 46, v124
	s_nop 0
	v_cndmask_b32_e32 v40, v108, v40, vcc
	v_cmp_le_i32_e32 vcc, v125, v96
	v_add_u32_e32 v125, -14, v124
	s_nop 0
	v_cndmask_b32_e32 v57, v108, v57, vcc
	v_cmp_le_i32_e32 vcc, v125, v96
	v_subrev_u32_e32 v125, 45, v124
	s_nop 0
	v_cndmask_b32_e32 v41, v108, v41, vcc
	v_cmp_le_i32_e32 vcc, v125, v96
	v_add_u32_e32 v125, -13, v124
	s_nop 0
	v_cndmask_b32_e32 v58, v108, v58, vcc
	v_cmp_le_i32_e32 vcc, v125, v96
	v_subrev_u32_e32 v125, 44, v124
	s_nop 0
	v_cndmask_b32_e32 v42, v108, v42, vcc
	v_cmp_le_i32_e32 vcc, v125, v96
	v_add_u32_e32 v125, -12, v124
	s_nop 0
	v_cndmask_b32_e32 v59, v108, v59, vcc
	v_cmp_le_i32_e32 vcc, v125, v96
	v_subrev_u32_e32 v125, 39, v124
	s_nop 0
	v_cndmask_b32_e32 v43, v108, v43, vcc
	v_cmp_le_i32_e32 vcc, v125, v96
	v_add_u32_e32 v125, -7, v124
	s_nop 0
	v_cndmask_b32_e32 v60, v108, v60, vcc
	v_cmp_le_i32_e32 vcc, v125, v96
	v_subrev_u32_e32 v125, 38, v124
	s_nop 0
	v_cndmask_b32_e32 v44, v108, v44, vcc
	v_cmp_le_i32_e32 vcc, v125, v96
	v_add_u32_e32 v125, -6, v124
	s_nop 0
	v_cndmask_b32_e32 v61, v108, v61, vcc
	v_cmp_le_i32_e32 vcc, v125, v96
	v_subrev_u32_e32 v125, 37, v124
	s_nop 0
	v_cndmask_b32_e32 v45, v108, v45, vcc
	v_cmp_le_i32_e32 vcc, v125, v96
	v_add_u32_e32 v125, -5, v124
	s_nop 0
	v_cndmask_b32_e32 v62, v108, v62, vcc
	v_cmp_le_i32_e32 vcc, v125, v96
	v_subrev_u32_e32 v125, 36, v124
	v_add_u32_e32 v124, -4, v124
	v_cndmask_b32_e32 v46, v108, v46, vcc
	v_cmp_le_i32_e32 vcc, v125, v96
	s_nop 1
	v_cndmask_b32_e32 v63, v108, v63, vcc
	v_cmp_le_i32_e32 vcc, v124, v96
	s_nop 1
	v_cndmask_b32_e32 v47, v108, v47, vcc

.LBB0_299:
	v_sub_f32_e32 v63, v63, v124
	v_sub_f32_e32 v62, v62, v124
	v_sub_f32_e32 v61, v61, v124
	v_sub_f32_e32 v60, v60, v124
	v_sub_f32_e32 v59, v59, v124
	v_sub_f32_e32 v58, v58, v124
	v_sub_f32_e32 v57, v57, v124
	v_sub_f32_e32 v56, v56, v124
	v_sub_f32_e32 v55, v55, v124
	v_sub_f32_e32 v54, v54, v124
	v_sub_f32_e32 v53, v53, v124
	v_sub_f32_e32 v52, v52, v124
	v_sub_f32_e32 v51, v51, v124
	v_sub_f32_e32 v50, v50, v124
	v_sub_f32_e32 v49, v49, v124
	v_sub_f32_e32 v48, v48, v124
	v_sub_f32_e32 v126, v47, v124
	v_sub_f32_e32 v127, v46, v124
	v_sub_f32_e32 v128, v45, v124
	v_sub_f32_e32 v129, v44, v124
	v_sub_f32_e32 v130, v43, v124
	v_sub_f32_e32 v131, v42, v124
	v_sub_f32_e32 v132, v41, v124
	v_sub_f32_e32 v133, v40, v124
	v_sub_f32_e32 v47, v39, v124
	v_sub_f32_e32 v39, v38, v124
	v_sub_f32_e32 v38, v37, v124
	v_sub_f32_e32 v37, v36, v124
	v_sub_f32_e32 v36, v35, v124
	v_sub_f32_e32 v35, v34, v124
	v_sub_f32_e32 v34, v33, v124
	v_sub_f32_e32 v33, v32, v124
	v_exp_f32_e32 v32, v48
	v_exp_f32_e32 v40, v33
	v_exp_f32_e32 v33, v49
	v_exp_f32_e32 v41, v34
	v_exp_f32_e32 v34, v50
	v_exp_f32_e32 v42, v35
	v_exp_f32_e32 v35, v51
	v_exp_f32_e32 v43, v36
	v_exp_f32_e32 v36, v52
	v_exp_f32_e32 v44, v37
	v_exp_f32_e32 v37, v53
	v_exp_f32_e32 v45, v38
	v_exp_f32_e32 v38, v54
	v_exp_f32_e32 v46, v39
	v_exp_f32_e32 v39, v55
	v_exp_f32_e32 v47, v47
	v_exp_f32_e32 v48, v56
	v_exp_f32_e32 v50, v133
	v_exp_f32_e32 v49, v57
	v_exp_f32_e32 v51, v132
	v_exp_f32_e32 v52, v58
	v_exp_f32_e32 v54, v131
	v_exp_f32_e32 v53, v59
	v_exp_f32_e32 v55, v130
	v_exp_f32_e32 v56, v60
	v_exp_f32_e32 v58, v129
	v_exp_f32_e32 v57, v61
	v_exp_f32_e32 v60, v62
	v_exp_f32_e32 v62, v127
	v_exp_f32_e32 v61, v63
	v_exp_f32_e32 v63, v126
	v_exp_f32_e32 v59, v128
	v_pk_add_f32 v[126:127], v[52:53], v[54:55]
	v_pk_add_f32 v[128:129], v[34:35], v[42:43]
	v_pk_add_f32 v[130:131], v[60:61], v[62:63]
	v_pk_add_f32 v[132:133], v[38:39], v[46:47]
	v_pk_add_f32 v[134:135], v[48:49], v[50:51]
	v_pk_add_f32 v[136:137], v[32:33], v[40:41]
	v_pk_add_f32 v[138:139], v[56:57], v[58:59]
	v_pk_add_f32 v[140:141], v[36:37], v[44:45]
	v_pk_add_f32 v[134:135], v[136:137], v[134:135]
	v_pk_add_f32 v[138:139], v[140:141], v[138:139]
	v_pk_add_f32 v[130:131], v[132:133], v[130:131]
	v_pk_add_f32 v[126:127], v[128:129], v[126:127]
	v_pk_add_f32 v[128:129], v[134:135], v[138:139]
	v_pk_add_f32 v[126:127], v[126:127], v[130:131]
	v_add_f32_e32 v128, v128, v129
	v_add_f32_e32 v126, v126, v127
	v_add_f32_e32 v126, v128, v126
	v_add_u32_e32 v125, s61, v116
	v_fmac_f32_e32 v126, v122, v123
	v_cvt_pk_bf16_f32 v32, v32, v33
	v_cvt_pk_bf16_f32 v33, v34, v35
	v_cvt_pk_bf16_f32 v34, v36, v37
	v_cvt_pk_bf16_f32 v35, v38, v39
	v_cvt_pk_bf16_f32 v36, v48, v49
	v_cvt_pk_bf16_f32 v37, v52, v53
	v_cvt_pk_bf16_f32 v38, v56, v57
	v_cvt_pk_bf16_f32 v39, v60, v61
	v_cvt_pk_bf16_f32 v40, v40, v41
	v_cvt_pk_bf16_f32 v41, v42, v43
	v_cvt_pk_bf16_f32 v42, v44, v45
	v_cvt_pk_bf16_f32 v43, v46, v47
	v_cvt_pk_bf16_f32 v44, v50, v51
	v_cvt_pk_bf16_f32 v45, v54, v55
	v_cvt_pk_bf16_f32 v46, v58, v59
	v_cvt_pk_bf16_f32 v47, v62, v63
	v_add3_u32 v52, v125, v112, v117
	ds_read_b64_tr_b16 v[216:217], v52 offset:8192
	ds_read_b64_tr_b16 v[218:219], v52 offset:8704
	ds_read_b64_tr_b16 v[220:221], v52 offset:9216
	ds_read_b64_tr_b16 v[222:223], v52 offset:9728
	s_waitcnt lgkmcnt(2)
	v_mfma_f32_32x32x16_bf16 v[0:15], v[32:35], v[216:219], v[0:15]
	ds_read_b64_tr_b16 v[216:217], v52 offset:10240
	ds_read_b64_tr_b16 v[218:219], v52 offset:10752
	s_waitcnt lgkmcnt(2)
	v_mfma_f32_32x32x16_bf16 v[0:15], v[36:39], v[220:223], v[0:15]
	ds_read_b64_tr_b16 v[220:221], v52 offset:11264
	ds_read_b64_tr_b16 v[222:223], v52 offset:11776
	s_waitcnt lgkmcnt(2)
	v_mfma_f32_32x32x16_bf16 v[0:15], v[40:43], v[216:219], v[0:15]
	ds_read_b64_tr_b16 v[216:217], v52 offset:12288
	ds_read_b64_tr_b16 v[218:219], v52 offset:12800
	s_waitcnt lgkmcnt(2)
	v_mfma_f32_32x32x16_bf16 v[0:15], v[44:47], v[220:223], v[0:15]
	ds_read_b64_tr_b16 v[220:221], v52 offset:13312
	ds_read_b64_tr_b16 v[222:223], v52 offset:13824
	s_waitcnt lgkmcnt(2)
	v_mfma_f32_32x32x16_bf16 v[16:31], v[32:35], v[216:219], v[16:31]
	ds_read_b64_tr_b16 v[216:217], v52 offset:14336
	ds_read_b64_tr_b16 v[218:219], v52 offset:14848
	s_waitcnt lgkmcnt(2)
	v_mfma_f32_32x32x16_bf16 v[16:31], v[36:39], v[220:223], v[16:31]
	ds_read_b64_tr_b16 v[220:221], v52 offset:15360
	ds_read_b64_tr_b16 v[222:223], v52 offset:15872
	s_waitcnt lgkmcnt(2)
	v_mfma_f32_32x32x16_bf16 v[16:31], v[40:43], v[216:219], v[16:31]
	s_waitcnt lgkmcnt(0)
	v_mfma_f32_32x32x16_bf16 v[16:31], v[44:47], v[220:223], v[16:31]
	s_mov_b32 s61, 0
	v_mov_b32_e32 v122, v126
	v_mov_b32_e32 v123, v124

.LBB0_314:
	s_barrier
	s_setprio 0
	s_load_dword s78, s[92:93], 0x130
	s_andn2_b64 vcc, exec, s[62:63]
	v_readlane_b32 s79, v254, 9
	s_cbranch_vccnz .LBB0_353
	v_mov_b32_e32 v0, v160
	s_nop 0
	v_readfirstlane_b32 s0, v0
	s_ashr_i32 s0, s0, 6
	s_add_i32 s0, s0, s91
	s_cmpk_gt_i32 s0, 0x7ff
	s_cbranch_scc1 .LBB0_334
	s_load_dwordx2 s[4:5], s[92:93], 0x40
	v_and_b32_e32 v1, 7, v0
	v_readlane_b32 s2, v254, 10
	v_lshlrev_b32_e32 v38, 2, v1
	v_bfe_u32 v39, v0, 3, 3
	v_lshlrev_b32_e32 v0, 4, v1
	v_mul_u32_u24_e32 v3, 0x420, v1
	v_mov_b32_e32 v1, 0
	v_readlane_b32 s3, v254, 11
	v_add_u32_e32 v2, s41, v0
	s_lshl_b32 s1, s0, 5
	v_lshl_add_u64 v[32:33], s[2:3], 0, v[0:1]
	v_lshlrev_b32_e32 v0, 2, v39
	v_add3_u32 v40, s41, v3, v0
	v_mul_u32_u24_e32 v0, 0x84, v39
	s_lshl_b32 s2, s34, 5
	s_movk_i32 s3, 0x1000
	v_add_u32_e32 v41, v2, v0
	s_branch .LBB0_318

.LBB0_3818:
	s_barrier
	v_readfirstlane_b32 s10, v160
	s_nop 3
	s_lshr_b32 s10, s10, 6
	s_cmp_ge_u32 s10, 4
	s_cbranch_scc0 .Lprio_done_nsa
	s_setprio 1
.Lprio_done_nsa:
	s_mov_b64 s[8:9], exec
	v_readlane_b32 s10, v254, 3
	v_readlane_b32 s11, v254, 4
	s_and_b64 s[10:11], s[8:9], s[10:11]
	s_mov_b64 exec, s[10:11]
	s_cbranch_execz .LBB0_3822
	s_mov_b64 s[12:13], exec
	v_mbcnt_lo_u32_b32 v1, s12, 0
	v_mbcnt_hi_u32_b32 v1, s13, v1
	v_cmp_eq_u32_e32 vcc, 0, v1
	s_and_saveexec_b64 s[10:11], vcc
	s_cbranch_execz .LBB0_3821
	s_bcnt1_i32_b64 s12, s[12:13]
	v_mov_b32_e32 v2, s12
	global_atomic_add v2, v0, v2, s[66:67] sc0

.LBB0_3831:
	s_add_i32 s13, s11, 0xffffc000
	s_and_b32 s13, s13, 0x4000
	v_add_u32_e32 v10, s13, v1
	ds_read_b128 v[2:5], v10
	ds_read_b128 v[6:9], v10 offset:512
	ds_read_b128 v[54:57], v10 offset:2048
	ds_read_b128 v[58:61], v10 offset:2560
	ds_read_b128 v[62:65], v10 offset:4096
	ds_read_b128 v[66:69], v10 offset:4608
	ds_read_b128 v[70:73], v10 offset:6144
	ds_read_b128 v[74:77], v10 offset:6656
	s_waitcnt lgkmcnt(7)
	v_mfma_f32_32x32x16_bf16 v[18:33], v[2:5], v[86:89], 0
	s_waitcnt lgkmcnt(6)
	v_mfma_f32_32x32x16_bf16 v[2:17], v[6:9], v[86:89], 0
	s_waitcnt lgkmcnt(5)
	v_mfma_f32_32x32x16_bf16 v[18:33], v[54:57], v[90:93], v[18:33]
	s_waitcnt lgkmcnt(4)
	v_mfma_f32_32x32x16_bf16 v[2:17], v[58:61], v[90:93], v[2:17]
	s_waitcnt lgkmcnt(3)
	v_mfma_f32_32x32x16_bf16 v[18:33], v[62:65], v[94:97], v[18:33]
	s_waitcnt lgkmcnt(2)
	v_mfma_f32_32x32x16_bf16 v[2:17], v[66:69], v[94:97], v[2:17]
	s_waitcnt lgkmcnt(1)
	v_mfma_f32_32x32x16_bf16 v[18:33], v[70:73], v[98:101], v[18:33]
	s_waitcnt lgkmcnt(0)
	v_mfma_f32_32x32x16_bf16 v[2:17], v[74:77], v[98:101], v[2:17]
	s_cmp_le_u32 s12, s14
	s_cbranch_scc1 .LBB0_3833
	v_add_u32_e32 v47, s12, v126
	v_add_u32_e32 v54, 0xfffffc10, v47
	v_cmp_le_i32_e32 vcc, v54, v128
	v_add_u32_e32 v54, 0xfffffe10, v47
	v_add_u32_e32 v53, 0xfffffbf1, v47
	s_nop 1
	v_cndmask_b32_e32 v18, v170, v18, vcc
	v_cmp_le_i32_e32 vcc, v54, v128
	v_add_u32_e32 v54, 0xfffffc20, v47
	s_nop 0
	v_cndmask_b32_e32 v2, v170, v2, vcc
	v_cmp_le_i32_e32 vcc, v54, v128
	v_add_u32_e32 v54, 0xfffffe20, v47
	s_nop 0
	v_cndmask_b32_e32 v19, v170, v19, vcc
	v_cmp_le_i32_e32 vcc, v54, v128
	v_add_u32_e32 v54, 0xfffffc30, v47
	s_nop 0
	v_cndmask_b32_e32 v3, v170, v3, vcc
	v_cmp_le_i32_e32 vcc, v54, v128
	v_add_u32_e32 v54, 0xfffffe30, v47
	s_nop 0
	v_cndmask_b32_e32 v20, v170, v20, vcc
	v_cmp_le_i32_e32 vcc, v54, v128
	v_add_u32_e32 v54, 0xfffffc90, v47
	s_nop 0
	v_cndmask_b32_e32 v4, v170, v4, vcc
	v_cmp_le_i32_e32 vcc, v53, v127
	s_nop 1
	v_cndmask_b32_e32 v21, v170, v21, vcc
	v_cmp_le_i32_e32 vcc, v53, v134
	s_nop 1
	v_cndmask_b32_e32 v5, v170, v5, vcc
	v_cmp_le_i32_e32 vcc, v54, v128
	v_add_u32_e32 v54, 0xfffffe90, v47
	s_nop 0
	v_cndmask_b32_e32 v22, v170, v22, vcc
	v_cmp_le_i32_e32 vcc, v54, v128
	v_add_u32_e32 v54, 0xfffffca0, v47
	s_nop 0
	v_cndmask_b32_e32 v6, v170, v6, vcc
	v_cmp_le_i32_e32 vcc, v54, v128
	v_add_u32_e32 v54, 0xfffffea0, v47
	s_nop 0
	v_cndmask_b32_e32 v23, v170, v23, vcc
	v_cmp_le_i32_e32 vcc, v54, v128
	v_add_u32_e32 v54, 0xfffffcb0, v47
	s_nop 0
	v_cndmask_b32_e32 v7, v170, v7, vcc
	v_cmp_le_i32_e32 vcc, v54, v128
	v_add_u32_e32 v54, 0xfffffeb0, v47
	s_nop 0
	v_cndmask_b32_e32 v24, v170, v24, vcc
	v_cmp_le_i32_e32 vcc, v54, v128
	v_add_u32_e32 v54, 0xfffffd10, v47
	s_nop 0
	v_cndmask_b32_e32 v8, v170, v8, vcc
	v_cmp_le_i32_e32 vcc, v53, v135
	s_nop 1
	v_cndmask_b32_e32 v25, v170, v25, vcc
	v_cmp_le_i32_e32 vcc, v53, v136
	s_nop 1
	v_cndmask_b32_e32 v9, v170, v9, vcc
	v_cmp_le_i32_e32 vcc, v54, v128
	v_add_u32_e32 v54, 0xffffff10, v47
	s_nop 0
	v_cndmask_b32_e32 v26, v170, v26, vcc
	v_cmp_le_i32_e32 vcc, v54, v128
	v_add_u32_e32 v54, 0xfffffd20, v47
	s_nop 0
	v_cndmask_b32_e32 v10, v170, v10, vcc
	v_cmp_le_i32_e32 vcc, v54, v128
	v_add_u32_e32 v54, 0xffffff20, v47
	s_nop 0
	v_cndmask_b32_e32 v27, v170, v27, vcc
	v_cmp_le_i32_e32 vcc, v54, v128
	v_add_u32_e32 v54, 0xfffffd30, v47
	s_nop 0
	v_cndmask_b32_e32 v11, v170, v11, vcc
	v_cmp_le_i32_e32 vcc, v54, v128
	v_add_u32_e32 v54, 0xffffff30, v47
	s_nop 0
	v_cndmask_b32_e32 v28, v170, v28, vcc
	v_cmp_le_i32_e32 vcc, v54, v128
	v_add_u32_e32 v54, 0xfffffd90, v47
	s_nop 0
	v_cndmask_b32_e32 v12, v170, v12, vcc
	v_cmp_le_i32_e32 vcc, v53, v137
	s_nop 1
	v_cndmask_b32_e32 v29, v170, v29, vcc
	v_cmp_le_i32_e32 vcc, v53, v138
	s_nop 1
	v_cndmask_b32_e32 v13, v170, v13, vcc
	v_cmp_le_i32_e32 vcc, v54, v128
	v_add_u32_e32 v54, 0xffffff90, v47
	s_nop 0
	v_cndmask_b32_e32 v30, v170, v30, vcc
	v_cmp_le_i32_e32 vcc, v54, v128
	v_add_u32_e32 v54, 0xfffffda0, v47
	s_nop 0
	v_cndmask_b32_e32 v14, v170, v14, vcc
	v_cmp_le_i32_e32 vcc, v54, v128
	v_add_u32_e32 v54, 0xffffffa0, v47
	s_nop 0
	v_cndmask_b32_e32 v31, v170, v31, vcc
	v_cmp_le_i32_e32 vcc, v54, v128
	v_add_u32_e32 v54, 0xfffffdb0, v47
	v_add_u32_e32 v47, 0xffffffb0, v47
	v_cndmask_b32_e32 v15, v170, v15, vcc
	v_cmp_le_i32_e32 vcc, v54, v128
	s_nop 1
	v_cndmask_b32_e32 v32, v170, v32, vcc
	v_cmp_le_i32_e32 vcc, v47, v128
	s_nop 1
	v_cndmask_b32_e32 v16, v170, v16, vcc
	v_cmp_le_i32_e32 vcc, v53, v139
	s_nop 1
	v_cndmask_b32_e32 v33, v170, v33, vcc
	v_cmp_le_i32_e32 vcc, v53, v140
	s_nop 1
	v_cndmask_b32_e32 v17, v170, v17, vcc

.LBB0_3842:
	s_and_b32 s12, s16, 0x4000
	s_add_i32 s20, s12, 0x100
	v_add3_u32 v58, s20, v177, v178
	ds_read_b128 v[50:53], v58
	ds_read_b128 v[54:57], v58 offset:512
	ds_read_b128 v[144:147], v58 offset:2048
	ds_read_b128 v[150:153], v58 offset:2560
	ds_read_b128 v[154:157], v58 offset:4096
	ds_read_b128 v[162:165], v58 offset:4608
	ds_read_b128 v[186:189], v58 offset:6144
	ds_read_b128 v[190:193], v58 offset:6656
	s_waitcnt lgkmcnt(7)
	v_mfma_f32_32x32x16_bf16 v[66:81], v[50:53], v[86:89], 0
	s_waitcnt lgkmcnt(6)
	v_mfma_f32_32x32x16_bf16 v[50:65], v[54:57], v[86:89], 0
	s_waitcnt lgkmcnt(5)
	v_mfma_f32_32x32x16_bf16 v[66:81], v[144:147], v[90:93], v[66:81]
	s_waitcnt lgkmcnt(4)
	v_mfma_f32_32x32x16_bf16 v[50:65], v[150:153], v[90:93], v[50:65]
	s_waitcnt lgkmcnt(3)
	v_mfma_f32_32x32x16_bf16 v[66:81], v[154:157], v[94:97], v[66:81]
	s_waitcnt lgkmcnt(2)
	v_mfma_f32_32x32x16_bf16 v[50:65], v[162:165], v[94:97], v[50:65]
	s_waitcnt lgkmcnt(1)
	v_mfma_f32_32x32x16_bf16 v[66:81], v[186:189], v[98:101], v[66:81]
	s_waitcnt lgkmcnt(0)
	v_mfma_f32_32x32x16_bf16 v[50:65], v[190:193], v[98:101], v[50:65]
	s_cmp_le_u32 s17, s14
	s_mov_b64 s[12:13], -1
	s_cbranch_scc0 .LBB0_3844
	s_nop 5
	v_sub_f32_e32 v144, v66, v34
	s_nop 0
	v_sub_f32_e32 v145, v50, v34
	v_sub_f32_e32 v146, v67, v1
	v_sub_f32_e32 v147, v51, v1
	v_sub_f32_e32 v148, v68, v36
	v_sub_f32_e32 v150, v52, v36
	v_sub_f32_e32 v151, v69, v35
	v_sub_f32_e32 v152, v53, v35
	v_sub_f32_e32 v153, v70, v38
	v_sub_f32_e32 v154, v54, v38
	v_sub_f32_e32 v155, v71, v37
	v_sub_f32_e32 v156, v55, v37
	v_sub_f32_e32 v157, v72, v40
	v_sub_f32_e32 v158, v56, v40
	v_sub_f32_e32 v159, v73, v39
	v_sub_f32_e32 v162, v57, v39
	v_sub_f32_e32 v163, v74, v42
	v_sub_f32_e32 v164, v58, v42
	v_sub_f32_e32 v165, v75, v41
	v_sub_f32_e32 v166, v59, v41
	v_sub_f32_e32 v167, v76, v44
	v_sub_f32_e32 v186, v60, v44
	v_sub_f32_e32 v187, v77, v43
	v_sub_f32_e32 v188, v61, v43
	v_sub_f32_e32 v189, v78, v46
	v_sub_f32_e32 v190, v62, v46
	v_sub_f32_e32 v191, v79, v45
	v_sub_f32_e32 v192, v63, v45
	v_sub_f32_e32 v193, v80, v48
	v_sub_f32_e32 v194, v64, v48
	v_sub_f32_e32 v195, v81, v47
	v_sub_f32_e32 v196, v65, v47
	v_exp_f32_e32 v144, v144
	v_exp_f32_e32 v145, v145
	v_exp_f32_e32 v146, v146
	v_exp_f32_e32 v147, v147
	v_exp_f32_e32 v148, v148
	v_exp_f32_e32 v150, v150
	v_exp_f32_e32 v151, v151
	v_exp_f32_e32 v152, v152
	v_exp_f32_e32 v153, v153
	v_exp_f32_e32 v154, v154
	v_exp_f32_e32 v155, v155
	v_exp_f32_e32 v156, v156
	v_exp_f32_e32 v157, v157
	v_exp_f32_e32 v158, v158
	v_exp_f32_e32 v159, v159
	v_exp_f32_e32 v162, v162
	v_exp_f32_e32 v163, v163
	v_exp_f32_e32 v164, v164
	v_exp_f32_e32 v165, v165
	v_exp_f32_e32 v166, v166
	v_exp_f32_e32 v167, v167
	v_exp_f32_e32 v186, v186
	v_exp_f32_e32 v187, v187
	v_exp_f32_e32 v188, v188
	v_exp_f32_e32 v189, v189
	v_exp_f32_e32 v190, v190
	v_exp_f32_e32 v191, v191
	v_exp_f32_e32 v192, v192
	v_exp_f32_e32 v193, v193
	v_exp_f32_e32 v194, v194
	v_exp_f32_e32 v195, v195
	v_exp_f32_e32 v196, v196
	s_mov_b64 s[12:13], 0

.LBB0_3848:
	s_or_b64 exec, exec, s[12:13]
	v_cvt_pk_bf16_f32 v50, v144, v146
	s_waitcnt lgkmcnt(14)
	v_cvt_pk_bf16_f32 v51, v148, v151
	v_cvt_pk_bf16_f32 v52, v153, v155
	v_cvt_pk_bf16_f32 v53, v157, v159
	v_cvt_pk_bf16_f32 v54, v163, v165
	s_waitcnt lgkmcnt(13)
	v_cvt_pk_bf16_f32 v55, v167, v187
	v_cvt_pk_bf16_f32 v56, v189, v191
	s_waitcnt lgkmcnt(12)
	v_cvt_pk_bf16_f32 v57, v193, v195
	s_waitcnt lgkmcnt(11)
	v_cvt_pk_bf16_f32 v60, v145, v147
	v_cvt_pk_bf16_f32 v61, v150, v152
	s_waitcnt lgkmcnt(10)
	v_cvt_pk_bf16_f32 v62, v154, v156
	v_cvt_pk_bf16_f32 v63, v158, v162
	s_waitcnt lgkmcnt(9)
	v_cvt_pk_bf16_f32 v64, v164, v166
	v_cvt_pk_bf16_f32 v65, v186, v188
	s_waitcnt lgkmcnt(8)
	v_cvt_pk_bf16_f32 v66, v190, v192
	s_waitcnt lgkmcnt(6)
	v_cvt_pk_bf16_f32 v67, v194, v196
	v_add_u32_e32 v59, s20, v181
	s_waitcnt lgkmcnt(0)
	ds_read_b64_tr_b16 v[216:217], v59 offset:8192
	ds_read_b64_tr_b16 v[218:219], v59 offset:8704
	ds_read_b64_tr_b16 v[220:221], v59 offset:9216
	ds_read_b64_tr_b16 v[222:223], v59 offset:9728
	s_waitcnt lgkmcnt(2)
	v_mfma_f32_32x32x16_bf16 v[2:17], v[50:53], v[216:219], v[2:17]
	ds_read_b64_tr_b16 v[216:217], v59 offset:10240
	ds_read_b64_tr_b16 v[218:219], v59 offset:10752
	s_waitcnt lgkmcnt(2)
	v_mfma_f32_32x32x16_bf16 v[2:17], v[54:57], v[220:223], v[2:17]
	ds_read_b64_tr_b16 v[220:221], v59 offset:11264
	ds_read_b64_tr_b16 v[222:223], v59 offset:11776
	s_waitcnt lgkmcnt(2)
	v_mfma_f32_32x32x16_bf16 v[2:17], v[60:63], v[216:219], v[2:17]
	ds_read_b64_tr_b16 v[216:217], v59 offset:12288
	ds_read_b64_tr_b16 v[218:219], v59 offset:12800
	s_waitcnt lgkmcnt(2)
	v_mfma_f32_32x32x16_bf16 v[2:17], v[64:67], v[220:223], v[2:17]
	ds_read_b64_tr_b16 v[220:221], v59 offset:13312
	ds_read_b64_tr_b16 v[222:223], v59 offset:13824
	s_waitcnt lgkmcnt(2)
	v_mfma_f32_32x32x16_bf16 v[18:33], v[50:53], v[216:219], v[18:33]
	ds_read_b64_tr_b16 v[216:217], v59 offset:14336
	ds_read_b64_tr_b16 v[218:219], v59 offset:14848
	s_waitcnt lgkmcnt(2)
	v_mfma_f32_32x32x16_bf16 v[18:33], v[54:57], v[220:223], v[18:33]
	ds_read_b64_tr_b16 v[220:221], v59 offset:15360
	ds_read_b64_tr_b16 v[222:223], v59 offset:15872
	s_waitcnt lgkmcnt(2)
	v_mfma_f32_32x32x16_bf16 v[18:33], v[60:63], v[216:219], v[18:33]
	s_waitcnt lgkmcnt(0)
	v_mfma_f32_32x32x16_bf16 v[18:33], v[64:67], v[220:223], v[18:33]
	s_add_i32 s19, s19, 1
	s_cmp_lt_u32 s19, s15
	s_mov_b64 s[12:13], -1
	s_cbranch_scc1 .LBB0_3850
	s_add_i32 s20, s16, 0x4000
	s_mov_b64 s[12:13], 0

.LBB0_4167:
	s_and_b32 s16, s15, 0x4000
	s_add_i32 s17, s16, 0x100
	v_add3_u32 v1, s17, v177, v178
	ds_read_b128 v[34:37], v1
	ds_read_b128 v[38:41], v1 offset:512
	ds_read_b128 v[108:111], v1 offset:2048
	ds_read_b128 v[112:115], v1 offset:2560
	ds_read_b128 v[116:119], v1 offset:4096
	ds_read_b128 v[120:123], v1 offset:4608
	ds_read_b128 v[136:139], v1 offset:6144
	ds_read_b128 v[140:143], v1 offset:6656
	s_waitcnt lgkmcnt(7)
	v_mfma_f32_32x32x16_bf16 v[50:65], v[34:37], v[86:89], 0
	s_waitcnt lgkmcnt(6)
	v_mfma_f32_32x32x16_bf16 v[34:49], v[38:41], v[86:89], 0
	s_waitcnt lgkmcnt(5)
	v_mfma_f32_32x32x16_bf16 v[50:65], v[108:111], v[90:93], v[50:65]
	s_waitcnt lgkmcnt(4)
	v_mfma_f32_32x32x16_bf16 v[34:49], v[112:115], v[90:93], v[34:49]
	s_waitcnt lgkmcnt(3)
	v_mfma_f32_32x32x16_bf16 v[50:65], v[116:119], v[94:97], v[50:65]
	s_waitcnt lgkmcnt(2)
	v_mfma_f32_32x32x16_bf16 v[34:49], v[120:123], v[94:97], v[34:49]
	s_waitcnt lgkmcnt(1)
	v_mfma_f32_32x32x16_bf16 v[50:65], v[136:139], v[98:101], v[50:65]
	s_waitcnt lgkmcnt(0)
	v_mfma_f32_32x32x16_bf16 v[34:49], v[140:143], v[98:101], v[34:49]
	s_cmp_lg_u32 s48, s13
	s_cselect_b64 s[10:11], -1, 0
	s_cmp_lg_u32 s12, s13
	s_cselect_b64 s[18:19], -1, 0
	s_and_b64 s[10:11], s[10:11], s[18:19]
	s_and_b64 vcc, exec, s[10:11]
	s_cbranch_vccnz .LBB0_4169
	v_add_u32_e32 v1, s14, v131
	v_add_u32_e32 v108, 0x200, v1
	v_cmp_le_u32_e32 vcc, v1, v128
	v_cmp_gt_u32_e64 s[10:11], v108, v128
	s_and_b64 vcc, vcc, s[10:11]
	v_add_u32_e32 v108, 32, v1
	v_cndmask_b32_e32 v50, v170, v50, vcc
	v_cmp_le_u32_e32 vcc, v108, v128
	v_add_u32_e32 v108, 0x220, v1
	v_cmp_gt_u32_e64 s[10:11], v108, v128
	s_and_b64 vcc, vcc, s[10:11]
	v_add_u32_e32 v108, 0x201, v1
	v_cndmask_b32_e32 v34, v170, v34, vcc
	v_cmp_lt_u32_e32 vcc, v1, v128
	v_cmp_gt_u32_e64 s[10:11], v108, v128
	s_and_b64 vcc, vcc, s[10:11]
	v_add_u32_e32 v108, 33, v1
	v_cndmask_b32_e32 v51, v170, v51, vcc
	v_cmp_le_u32_e32 vcc, v108, v128
	v_add_u32_e32 v108, 0x221, v1
	v_cmp_gt_u32_e64 s[10:11], v108, v128
	s_and_b64 vcc, vcc, s[10:11]
	v_add_u32_e32 v108, 2, v1
	v_cndmask_b32_e32 v35, v170, v35, vcc
	v_cmp_le_u32_e32 vcc, v108, v128
	v_add_u32_e32 v108, 0x202, v1
	v_cmp_gt_u32_e64 s[10:11], v108, v128
	s_and_b64 vcc, vcc, s[10:11]
	v_add_u32_e32 v108, 34, v1
	v_cndmask_b32_e32 v52, v170, v52, vcc
	v_cmp_le_u32_e32 vcc, v108, v128
	v_add_u32_e32 v108, 0x222, v1
	v_cmp_gt_u32_e64 s[10:11], v108, v128
	s_and_b64 vcc, vcc, s[10:11]
	v_add_u32_e32 v108, 3, v1
	v_cndmask_b32_e32 v36, v170, v36, vcc
	v_cmp_le_u32_e32 vcc, v108, v128
	v_add_u32_e32 v108, 0x203, v1
	v_cmp_gt_u32_e64 s[10:11], v108, v128
	s_and_b64 vcc, vcc, s[10:11]
	v_add_u32_e32 v108, 35, v1
	v_cndmask_b32_e32 v53, v170, v53, vcc
	v_cmp_le_u32_e32 vcc, v108, v128
	v_add_u32_e32 v108, 0x223, v1
	v_cmp_gt_u32_e64 s[10:11], v108, v128
	s_and_b64 vcc, vcc, s[10:11]
	v_add_u32_e32 v108, 8, v1
	v_cndmask_b32_e32 v37, v170, v37, vcc
	v_cmp_le_u32_e32 vcc, v108, v128
	v_add_u32_e32 v108, 0x208, v1
	v_cmp_gt_u32_e64 s[10:11], v108, v128
	s_and_b64 vcc, vcc, s[10:11]
	v_add_u32_e32 v108, 40, v1
	v_cndmask_b32_e32 v54, v170, v54, vcc
	v_cmp_le_u32_e32 vcc, v108, v128
	v_add_u32_e32 v108, 0x228, v1
	v_cmp_gt_u32_e64 s[10:11], v108, v128
	s_and_b64 vcc, vcc, s[10:11]
	v_add_u32_e32 v108, 9, v1
	v_cndmask_b32_e32 v38, v170, v38, vcc
	v_cmp_le_u32_e32 vcc, v108, v128
	v_add_u32_e32 v108, 0x209, v1
	v_cmp_gt_u32_e64 s[10:11], v108, v128
	s_and_b64 vcc, vcc, s[10:11]
	v_add_u32_e32 v108, 41, v1
	v_cndmask_b32_e32 v55, v170, v55, vcc
	v_cmp_le_u32_e32 vcc, v108, v128
	v_add_u32_e32 v108, 0x229, v1
	v_cmp_gt_u32_e64 s[10:11], v108, v128
	s_and_b64 vcc, vcc, s[10:11]
	v_add_u32_e32 v108, 10, v1
	v_cndmask_b32_e32 v39, v170, v39, vcc
	v_cmp_le_u32_e32 vcc, v108, v128
	v_add_u32_e32 v108, 0x20a, v1
	v_cmp_gt_u32_e64 s[10:11], v108, v128
	s_and_b64 vcc, vcc, s[10:11]
	v_add_u32_e32 v108, 42, v1
	v_cndmask_b32_e32 v56, v170, v56, vcc
	v_cmp_le_u32_e32 vcc, v108, v128
	v_add_u32_e32 v108, 0x22a, v1
	v_cmp_gt_u32_e64 s[10:11], v108, v128
	s_and_b64 vcc, vcc, s[10:11]
	v_add_u32_e32 v108, 11, v1
	v_cndmask_b32_e32 v40, v170, v40, vcc
	v_cmp_le_u32_e32 vcc, v108, v128
	v_add_u32_e32 v108, 0x20b, v1
	v_cmp_gt_u32_e64 s[10:11], v108, v128
	s_and_b64 vcc, vcc, s[10:11]
	v_add_u32_e32 v108, 43, v1
	v_cndmask_b32_e32 v57, v170, v57, vcc
	v_cmp_le_u32_e32 vcc, v108, v128
	v_add_u32_e32 v108, 0x22b, v1
	v_cmp_gt_u32_e64 s[10:11], v108, v128
	s_and_b64 vcc, vcc, s[10:11]
	v_add_u32_e32 v108, 16, v1
	v_cndmask_b32_e32 v41, v170, v41, vcc
	v_cmp_le_u32_e32 vcc, v108, v128
	v_add_u32_e32 v108, 0x210, v1
	v_cmp_gt_u32_e64 s[10:11], v108, v128
	s_and_b64 vcc, vcc, s[10:11]
	v_add_u32_e32 v108, 48, v1
	v_cndmask_b32_e32 v58, v170, v58, vcc
	v_cmp_le_u32_e32 vcc, v108, v128
	v_add_u32_e32 v108, 0x230, v1
	v_cmp_gt_u32_e64 s[10:11], v108, v128
	s_and_b64 vcc, vcc, s[10:11]
	v_add_u32_e32 v108, 17, v1
	v_cndmask_b32_e32 v42, v170, v42, vcc
	v_cmp_le_u32_e32 vcc, v108, v128
	v_add_u32_e32 v108, 0x211, v1
	v_cmp_gt_u32_e64 s[10:11], v108, v128
	s_and_b64 vcc, vcc, s[10:11]
	v_add_u32_e32 v108, 49, v1
	v_cndmask_b32_e32 v59, v170, v59, vcc
	v_cmp_le_u32_e32 vcc, v108, v128
	v_add_u32_e32 v108, 0x231, v1
	v_cmp_gt_u32_e64 s[10:11], v108, v128
	s_and_b64 vcc, vcc, s[10:11]
	v_add_u32_e32 v108, 18, v1
	v_cndmask_b32_e32 v43, v170, v43, vcc
	v_cmp_le_u32_e32 vcc, v108, v128
	v_add_u32_e32 v108, 0x212, v1
	v_cmp_gt_u32_e64 s[10:11], v108, v128
	s_and_b64 vcc, vcc, s[10:11]
	v_add_u32_e32 v108, 50, v1
	v_cndmask_b32_e32 v60, v170, v60, vcc
	v_cmp_le_u32_e32 vcc, v108, v128
	v_add_u32_e32 v108, 0x232, v1
	v_cmp_gt_u32_e64 s[10:11], v108, v128
	s_and_b64 vcc, vcc, s[10:11]
	v_add_u32_e32 v108, 19, v1
	v_cndmask_b32_e32 v44, v170, v44, vcc
	v_cmp_le_u32_e32 vcc, v108, v128
	v_add_u32_e32 v108, 0x213, v1
	v_cmp_gt_u32_e64 s[10:11], v108, v128
	s_and_b64 vcc, vcc, s[10:11]
	v_add_u32_e32 v108, 51, v1
	v_cndmask_b32_e32 v61, v170, v61, vcc
	v_cmp_le_u32_e32 vcc, v108, v128
	v_add_u32_e32 v108, 0x233, v1
	v_cmp_gt_u32_e64 s[10:11], v108, v128
	s_and_b64 vcc, vcc, s[10:11]
	v_add_u32_e32 v108, 24, v1
	v_cndmask_b32_e32 v45, v170, v45, vcc
	v_cmp_le_u32_e32 vcc, v108, v128
	v_add_u32_e32 v108, 0x218, v1
	v_cmp_gt_u32_e64 s[10:11], v108, v128
	s_and_b64 vcc, vcc, s[10:11]
	v_add_u32_e32 v108, 56, v1
	v_cndmask_b32_e32 v62, v170, v62, vcc
	v_cmp_le_u32_e32 vcc, v108, v128
	v_add_u32_e32 v108, 0x238, v1
	v_cmp_gt_u32_e64 s[10:11], v108, v128
	s_and_b64 vcc, vcc, s[10:11]
	v_add_u32_e32 v108, 25, v1
	v_cndmask_b32_e32 v46, v170, v46, vcc
	v_cmp_le_u32_e32 vcc, v108, v128
	v_add_u32_e32 v108, 0x219, v1
	v_cmp_gt_u32_e64 s[10:11], v108, v128
	s_and_b64 vcc, vcc, s[10:11]
	v_add_u32_e32 v108, 57, v1
	v_cndmask_b32_e32 v63, v170, v63, vcc
	v_cmp_le_u32_e32 vcc, v108, v128
	v_add_u32_e32 v108, 0x239, v1
	v_cmp_gt_u32_e64 s[10:11], v108, v128
	s_and_b64 vcc, vcc, s[10:11]
	v_add_u32_e32 v108, 26, v1
	v_cndmask_b32_e32 v47, v170, v47, vcc
	v_cmp_le_u32_e32 vcc, v108, v128
	v_add_u32_e32 v108, 0x21a, v1
	v_cmp_gt_u32_e64 s[10:11], v108, v128
	s_and_b64 vcc, vcc, s[10:11]
	v_add_u32_e32 v108, 58, v1
	v_cndmask_b32_e32 v64, v170, v64, vcc
	v_cmp_le_u32_e32 vcc, v108, v128
	v_add_u32_e32 v108, 0x23a, v1
	v_cmp_gt_u32_e64 s[10:11], v108, v128
	s_and_b64 vcc, vcc, s[10:11]
	v_add_u32_e32 v108, 27, v1
	v_cndmask_b32_e32 v48, v170, v48, vcc
	v_cmp_le_u32_e32 vcc, v108, v128
	v_add_u32_e32 v108, 0x21b, v1
	v_cmp_gt_u32_e64 s[10:11], v108, v128
	s_and_b64 vcc, vcc, s[10:11]
	v_add_u32_e32 v108, 59, v1
	v_add_u32_e32 v1, 0x23b, v1
	v_cndmask_b32_e32 v65, v170, v65, vcc
	v_cmp_le_u32_e32 vcc, v108, v128
	v_cmp_gt_u32_e64 s[10:11], v1, v128
	s_and_b64 vcc, vcc, s[10:11]
	v_cndmask_b32_e32 v49, v170, v49, vcc

.LBB0_4173:
	v_sub_f32_e32 v108, v65, v1
	v_sub_f32_e32 v109, v64, v1
	v_sub_f32_e32 v110, v63, v1
	v_sub_f32_e32 v111, v62, v1
	v_sub_f32_e32 v61, v61, v1
	v_sub_f32_e32 v60, v60, v1
	v_sub_f32_e32 v59, v59, v1
	v_sub_f32_e32 v58, v58, v1
	v_sub_f32_e32 v57, v57, v1
	v_sub_f32_e32 v56, v56, v1
	v_sub_f32_e32 v55, v55, v1
	v_sub_f32_e32 v54, v54, v1
	v_sub_f32_e32 v53, v53, v1
	v_sub_f32_e32 v52, v52, v1
	v_sub_f32_e32 v51, v51, v1
	v_sub_f32_e32 v50, v50, v1
	v_sub_f32_e32 v112, v49, v1
	v_sub_f32_e32 v113, v48, v1
	v_sub_f32_e32 v114, v47, v1
	v_sub_f32_e32 v115, v46, v1
	v_sub_f32_e32 v116, v45, v1
	v_sub_f32_e32 v117, v44, v1
	v_sub_f32_e32 v65, v43, v1
	v_sub_f32_e32 v63, v42, v1
	v_sub_f32_e32 v45, v41, v1
	v_sub_f32_e32 v43, v40, v1
	v_sub_f32_e32 v41, v39, v1
	v_sub_f32_e32 v39, v38, v1
	v_sub_f32_e32 v38, v37, v1
	v_sub_f32_e32 v40, v36, v1
	v_sub_f32_e32 v37, v35, v1
	v_sub_f32_e32 v35, v34, v1
	v_exp_f32_e32 v34, v50
	v_exp_f32_e32 v36, v35
	v_exp_f32_e32 v35, v51
	v_exp_f32_e32 v37, v37
	v_exp_f32_e32 v46, v52
	v_exp_f32_e32 v48, v40
	v_exp_f32_e32 v47, v53
	v_exp_f32_e32 v49, v38
	v_exp_f32_e32 v38, v54
	v_exp_f32_e32 v40, v39
	v_exp_f32_e32 v39, v55
	v_exp_f32_e32 v41, v41
	v_exp_f32_e32 v42, v56
	v_exp_f32_e32 v44, v43
	v_exp_f32_e32 v43, v57
	v_exp_f32_e32 v45, v45
	v_exp_f32_e32 v62, v58
	v_exp_f32_e32 v64, v63
	v_exp_f32_e32 v63, v59
	v_exp_f32_e32 v65, v65
	v_exp_f32_e32 v58, v60
	v_exp_f32_e32 v60, v117
	v_exp_f32_e32 v59, v61
	v_exp_f32_e32 v61, v116
	v_exp_f32_e32 v50, v111
	v_exp_f32_e32 v52, v115
	v_exp_f32_e32 v51, v110
	v_exp_f32_e32 v53, v114
	v_exp_f32_e32 v54, v109
	v_exp_f32_e32 v56, v113
	v_exp_f32_e32 v55, v108
	v_exp_f32_e32 v57, v112
	v_cvt_pk_bf16_f32 v108, v34, v35
	v_cvt_pk_bf16_f32 v109, v46, v47
	v_cvt_pk_bf16_f32 v110, v38, v39
	v_cvt_pk_bf16_f32 v111, v42, v43
	v_cvt_pk_bf16_f32 v112, v62, v63
	v_cvt_pk_bf16_f32 v113, v58, v59
	v_cvt_pk_bf16_f32 v114, v50, v51
	v_cvt_pk_bf16_f32 v115, v54, v55
	v_cvt_pk_bf16_f32 v116, v36, v37
	v_cvt_pk_bf16_f32 v117, v48, v49
	v_cvt_pk_bf16_f32 v118, v40, v41
	v_cvt_pk_bf16_f32 v119, v44, v45
	v_cvt_pk_bf16_f32 v120, v64, v65
	v_cvt_pk_bf16_f32 v121, v60, v61
	v_cvt_pk_bf16_f32 v122, v52, v53
	v_cvt_pk_bf16_f32 v123, v56, v57
	v_add_u32_e32 v124, s17, v181
	ds_read_b64_tr_b16 v[216:217], v124 offset:8192
	ds_read_b64_tr_b16 v[218:219], v124 offset:8704
	ds_read_b64_tr_b16 v[220:221], v124 offset:9216
	ds_read_b64_tr_b16 v[222:223], v124 offset:9728
	s_waitcnt lgkmcnt(2)
	v_mfma_f32_32x32x16_bf16 v[2:17], v[108:111], v[216:219], v[2:17]
	ds_read_b64_tr_b16 v[216:217], v124 offset:10240
	ds_read_b64_tr_b16 v[218:219], v124 offset:10752
	s_waitcnt lgkmcnt(2)
	v_mfma_f32_32x32x16_bf16 v[2:17], v[112:115], v[220:223], v[2:17]
	ds_read_b64_tr_b16 v[220:221], v124 offset:11264
	ds_read_b64_tr_b16 v[222:223], v124 offset:11776
	s_waitcnt lgkmcnt(2)
	v_mfma_f32_32x32x16_bf16 v[2:17], v[116:119], v[216:219], v[2:17]
	ds_read_b64_tr_b16 v[216:217], v124 offset:12288
	ds_read_b64_tr_b16 v[218:219], v124 offset:12800
	s_waitcnt lgkmcnt(2)
	v_mfma_f32_32x32x16_bf16 v[2:17], v[120:123], v[220:223], v[2:17]
	ds_read_b64_tr_b16 v[220:221], v124 offset:13312
	ds_read_b64_tr_b16 v[222:223], v124 offset:13824
	s_waitcnt lgkmcnt(2)
	v_mfma_f32_32x32x16_bf16 v[18:33], v[108:111], v[216:219], v[18:33]
	ds_read_b64_tr_b16 v[216:217], v124 offset:14336
	ds_read_b64_tr_b16 v[218:219], v124 offset:14848
	s_waitcnt lgkmcnt(2)
	v_mfma_f32_32x32x16_bf16 v[18:33], v[112:115], v[220:223], v[18:33]
	ds_read_b64_tr_b16 v[220:221], v124 offset:15360
	ds_read_b64_tr_b16 v[222:223], v124 offset:15872
	s_waitcnt lgkmcnt(2)
	v_mfma_f32_32x32x16_bf16 v[18:33], v[116:119], v[216:219], v[18:33]
	s_waitcnt lgkmcnt(0)
	v_mfma_f32_32x32x16_bf16 v[18:33], v[120:123], v[220:223], v[18:33]
	s_cmp_ge_u32 s13, s48
	s_cselect_b64 s[10:11], -1, 0
	s_and_b64 vcc, exec, s[10:11]
	s_cbranch_vccnz .LBB0_4175
	s_xor_b32 s16, s16, 0x4000
	v_add_u32_e32 v108, s16, v182
	ds_write_b128 v108, v[74:77]
	ds_write_b128 v108, v[78:81] offset:8192
